# carried HGRN2 / retention states of the decode group (read once, written once) moved with the non-temporal hint
# speedup vs baseline: 1.0020x; 1.0020x over previous
.LBB0_119:
	s_mov_b64 s[0:1], s[58:59]
	s_load_dwordx2 s[16:17], s[0:1], 0x158
	s_mov_b64 s[0:1], s[58:59]
	s_load_dwordx2 s[18:19], s[0:1], 0x20
	s_mov_b64 s[0:1], s[58:59]
	s_load_dwordx2 s[4:5], s[0:1], 0x150
	s_mov_b64 s[0:1], s[58:59]
	s_load_dwordx2 s[6:7], s[0:1], 0xa8
	s_mov_b64 s[0:1], s[58:59]
	s_load_dwordx2 s[10:11], s[0:1], 0x158
	v_mbcnt_lo_u32_b32 v1, -1, 0
	v_mbcnt_hi_u32_b32 v1, -1, v1
	s_lshl_b32 s1, s2, 1
	v_add_u32_e32 v116, s61, v1
	s_and_b32 s1, s1, -8
	s_ashr_i32 s3, s2, 31
	v_ashrrev_i32_e32 v98, 2, v116
	s_and_b32 s0, s2, 3
	s_add_i32 s14, s1, 0x4000
	s_lshl_b64 s[12:13], s[2:3], 14
	s_lshl_b64 s[20:21], s[2:3], 16
	v_and_b32_e32 v102, 0xffffffe0, v98
	s_waitcnt lgkmcnt(0)
	s_add_u32 s18, s18, s20
	v_and_b32_e32 v0, 0x7f, v116
	v_or_b32_e32 v4, 1, v102
	v_or_b32_e32 v6, 2, v102
	v_or_b32_e32 v8, 3, v102
	v_or_b32_e32 v12, 5, v102
	v_or_b32_e32 v14, 6, v102
	s_addc_u32 s19, s19, s21
	v_lshlrev_b32_e32 v156, 2, v0
	v_ashrrev_i32_e32 v103, 31, v102
	v_ashrrev_i32_e32 v5, 31, v4
	v_ashrrev_i32_e32 v7, 31, v6
	v_ashrrev_i32_e32 v9, 31, v8
	v_or_b32_e32 v10, 4, v102
	v_ashrrev_i32_e32 v13, 31, v12
	v_ashrrev_i32_e32 v15, 31, v14
	v_or_b32_e32 v16, 7, v102
	v_lshl_add_u64 v[94:95], s[18:19], 0, v[156:157]
	v_lshlrev_b64 v[2:3], 9, v[102:103]
	v_lshlrev_b64 v[4:5], 9, v[4:5]
	v_lshlrev_b64 v[6:7], 9, v[6:7]
	v_lshlrev_b64 v[8:9], 9, v[8:9]
	v_ashrrev_i32_e32 v11, 31, v10
	v_lshlrev_b64 v[12:13], 9, v[12:13]
	v_lshlrev_b64 v[14:15], 9, v[14:15]
	v_ashrrev_i32_e32 v17, 31, v16
	v_lshl_add_u64 v[18:19], v[94:95], 0, v[2:3]
	v_lshl_add_u64 v[20:21], v[94:95], 0, v[4:5]
	v_lshl_add_u64 v[22:23], v[94:95], 0, v[6:7]
	v_lshl_add_u64 v[24:25], v[94:95], 0, v[8:9]
	v_lshlrev_b64 v[10:11], 9, v[10:11]
	v_lshl_add_u64 v[30:31], v[94:95], 0, v[12:13]
	v_lshl_add_u64 v[32:33], v[94:95], 0, v[14:15]
	v_lshlrev_b64 v[16:17], 9, v[16:17]
	v_lshl_add_u64 v[28:29], v[94:95], 0, v[10:11]
	v_lshl_add_u64 v[34:35], v[94:95], 0, v[16:17]
	global_load_dword v26, v[18:19], off nt
	global_load_dword v27, v[20:21], off nt
	s_nop 0
	global_load_dword v22, v[22:23], off nt
	s_nop 0
	global_load_dword v23, v[24:25], off nt
	global_load_dword v20, v[28:29], off nt
	global_load_dword v21, v[30:31], off nt
	global_load_dword v18, v[32:33], off nt
	global_load_dword v19, v[34:35], off nt
	v_or_b32_e32 v24, 8, v102
	v_or_b32_e32 v30, 10, v102
	v_or_b32_e32 v32, 11, v102
	v_or_b32_e32 v42, 14, v102
	v_or_b32_e32 v44, 15, v102
	v_ashrrev_i32_e32 v25, 31, v24
	v_or_b32_e32 v28, 9, v102
	v_ashrrev_i32_e32 v31, 31, v30
	v_ashrrev_i32_e32 v33, 31, v32
	v_or_b32_e32 v38, 12, v102
	v_or_b32_e32 v40, 13, v102
	v_ashrrev_i32_e32 v43, 31, v42
	v_ashrrev_i32_e32 v45, 31, v44
	v_lshlrev_b64 v[24:25], 9, v[24:25]
	v_ashrrev_i32_e32 v29, 31, v28
	v_lshlrev_b64 v[30:31], 9, v[30:31]
	v_lshlrev_b64 v[32:33], 9, v[32:33]
	v_ashrrev_i32_e32 v39, 31, v38
	v_ashrrev_i32_e32 v41, 31, v40
	v_lshlrev_b64 v[42:43], 9, v[42:43]
	v_lshlrev_b64 v[44:45], 9, v[44:45]
	v_lshl_add_u64 v[34:35], v[94:95], 0, v[24:25]
	v_lshlrev_b64 v[28:29], 9, v[28:29]
	v_lshl_add_u64 v[46:47], v[94:95], 0, v[30:31]
	v_lshl_add_u64 v[48:49], v[94:95], 0, v[32:33]
	v_lshlrev_b64 v[38:39], 9, v[38:39]
	v_lshlrev_b64 v[40:41], 9, v[40:41]
	v_lshl_add_u64 v[58:59], v[94:95], 0, v[42:43]
	v_lshl_add_u64 v[60:61], v[94:95], 0, v[44:45]
	v_lshl_add_u64 v[36:37], v[94:95], 0, v[28:29]
	v_lshl_add_u64 v[52:53], v[94:95], 0, v[38:39]
	v_lshl_add_u64 v[56:57], v[94:95], 0, v[40:41]
	global_load_dword v54, v[34:35], off nt
	global_load_dword v55, v[36:37], off nt
	global_load_dword v50, v[46:47], off nt
	global_load_dword v51, v[48:49], off nt
	s_nop 0
	global_load_dword v48, v[52:53], off nt
	global_load_dword v49, v[56:57], off nt
	global_load_dword v46, v[58:59], off nt
	global_load_dword v47, v[60:61], off nt
	v_or_b32_e32 v34, 16, v102
	v_or_b32_e32 v58, 18, v102
	v_or_b32_e32 v60, 19, v102
	v_ashrrev_i32_e32 v35, 31, v34
	v_or_b32_e32 v36, 17, v102
	v_ashrrev_i32_e32 v59, 31, v58
	v_ashrrev_i32_e32 v61, 31, v60
	v_or_b32_e32 v62, 20, v102
	v_or_b32_e32 v64, 21, v102
	v_or_b32_e32 v66, 22, v102
	v_or_b32_e32 v68, 23, v102
	v_lshlrev_b64 v[52:53], 9, v[34:35]
	v_ashrrev_i32_e32 v37, 31, v36
	v_lshlrev_b64 v[58:59], 9, v[58:59]
	v_lshlrev_b64 v[60:61], 9, v[60:61]
	v_ashrrev_i32_e32 v63, 31, v62
	v_ashrrev_i32_e32 v65, 31, v64
	v_ashrrev_i32_e32 v67, 31, v66
	v_ashrrev_i32_e32 v69, 31, v68
	v_lshl_add_u64 v[34:35], v[94:95], 0, v[52:53]
	v_lshlrev_b64 v[56:57], 9, v[36:37]
	v_lshl_add_u64 v[70:71], v[94:95], 0, v[58:59]
	v_lshl_add_u64 v[72:73], v[94:95], 0, v[60:61]
	v_lshlrev_b64 v[62:63], 9, v[62:63]
	v_lshlrev_b64 v[64:65], 9, v[64:65]
	v_lshlrev_b64 v[66:67], 9, v[66:67]
	v_lshlrev_b64 v[68:69], 9, v[68:69]
	v_lshl_add_u64 v[36:37], v[94:95], 0, v[56:57]
	v_lshl_add_u64 v[76:77], v[94:95], 0, v[62:63]
	v_lshl_add_u64 v[80:81], v[94:95], 0, v[64:65]
	v_lshl_add_u64 v[82:83], v[94:95], 0, v[66:67]
	v_lshl_add_u64 v[84:85], v[94:95], 0, v[68:69]
	global_load_dword v78, v[34:35], off nt
	global_load_dword v79, v[36:37], off nt
	global_load_dword v74, v[70:71], off nt
	global_load_dword v75, v[72:73], off nt
	s_nop 0
	global_load_dword v72, v[76:77], off nt
	global_load_dword v73, v[80:81], off nt
	global_load_dword v70, v[82:83], off nt
	global_load_dword v71, v[84:85], off nt
	v_or_b32_e32 v34, 24, v102
	v_ashrrev_i32_e32 v35, 31, v34
	v_lshlrev_b64 v[76:77], 9, v[34:35]
	v_or_b32_e32 v34, 25, v102
	v_ashrrev_i32_e32 v35, 31, v34
	v_lshlrev_b64 v[80:81], 9, v[34:35]
	v_or_b32_e32 v34, 26, v102
	v_ashrrev_i32_e32 v35, 31, v34
	v_ashrrev_i32_e32 v36, 6, v116
	v_lshlrev_b64 v[82:83], 9, v[34:35]
	v_and_b32_e32 v34, 63, v1
	v_add_u32_e32 v1, s14, v36
	v_mov_b64_e32 v[86:87], s[16:17]
	v_mad_i64_i32 v[86:87], s[16:17], v1, s83, v[86:87]
	s_lshl_b32 s30, s0, 8
	v_lshl_add_u64 v[86:87], v[86:87], 0, s[30:31]
	v_lshlrev_b32_e32 v88, 1, v34
	v_mov_b32_e32 v89, v157
	v_lshl_add_u64 v[86:87], v[86:87], 0, v[88:89]
	s_mov_b32 s1, 0x12f00000
	v_lshl_add_u64 v[92:93], v[86:87], 0, s[46:47]
	v_add_co_u32_e32 v86, vcc, s1, v86
	v_or_b32_e32 v84, 27, v102
	s_nop 0
	v_addc_co_u32_e32 v87, vcc, 0, v87, vcc
	global_load_ushort v1, v[86:87], off
	global_load_ushort v35, v[92:93], off offset:128
	global_load_ushort v37, v[92:93], off offset:1024
	global_load_ushort v103, v[92:93], off offset:1152
	v_or_b32_e32 v86, 28, v102
	v_or_b32_e32 v88, 29, v102
	v_or_b32_e32 v90, 30, v102
	v_or_b32_e32 v98, 31, v98
	v_ashrrev_i32_e32 v85, 31, v84
	v_ashrrev_i32_e32 v87, 31, v86
	v_ashrrev_i32_e32 v89, 31, v88
	v_ashrrev_i32_e32 v91, 31, v90
	v_ashrrev_i32_e32 v99, 31, v98
	v_lshl_add_u64 v[96:97], v[94:95], 0, v[76:77]
	v_lshl_add_u64 v[100:101], v[94:95], 0, v[80:81]
	v_lshl_add_u64 v[104:105], v[94:95], 0, v[82:83]
	v_lshlrev_b64 v[84:85], 9, v[84:85]
	v_lshlrev_b64 v[86:87], 9, v[86:87]
	v_lshlrev_b64 v[88:89], 9, v[88:89]
	v_lshlrev_b64 v[90:91], 9, v[90:91]
	global_load_ushort v117, v[92:93], off offset:2048
	global_load_ushort v118, v[92:93], off offset:2176
	global_load_ushort v119, v[92:93], off offset:3072
	global_load_ushort v120, v[92:93], off offset:3200
	v_lshlrev_b64 v[92:93], 9, v[98:99]
	v_lshl_add_u64 v[106:107], v[94:95], 0, v[84:85]
	v_lshl_add_u64 v[108:109], v[94:95], 0, v[86:87]
	v_lshl_add_u64 v[110:111], v[94:95], 0, v[88:89]
	v_lshl_add_u64 v[112:113], v[94:95], 0, v[90:91]
	v_lshl_add_u64 v[114:115], v[94:95], 0, v[92:93]
	global_load_dword v98, v[96:97], off nt
	global_load_dword v99, v[100:101], off nt
	s_nop 0
	global_load_dword v96, v[104:105], off nt
	global_load_dword v97, v[106:107], off nt
	global_load_dword v94, v[108:109], off nt
	global_load_dword v95, v[110:111], off nt
	global_load_dword v100, v[112:113], off nt
	s_nop 0
	global_load_dword v104, v[114:115], off nt
	v_lshlrev_b32_e32 v110, 2, v34
	v_add_u32_e32 v106, 0, v110
	v_add_u32_e32 v106, 0x22400, v106
	v_add_u32_e32 v105, 0x4000, v36
	ds_read_b32 v106, v106
	v_cvt_f32_i32_e32 v105, v105
	v_cvt_f32_ubyte0_e32 v101, s0
	v_sub_f32_e32 v101, 0xc0a00000, v101
	v_exp_f32_e32 v101, v101
	s_waitcnt lgkmcnt(0)
	v_mul_f32_e32 v105, v106, v105
	v_cvt_f64_f32_e32 v[106:107], v105
	v_mul_f64 v[108:109], v[106:107], s[86:87]
	v_rndne_f64_e32 v[108:109], v[108:109]
	v_fma_f64 v[106:107], v[106:107], s[86:87], -v[108:109]
	v_cvt_f32_f64_e32 v105, v[106:107]
	v_sin_f32_e32 v106, v105
	v_cos_f32_e32 v105, v105
	v_lshl_or_b32 v108, v36, 9, v110
	v_add_u32_e32 v108, 0, v108
	v_sub_f32_e32 v101, 1.0, v101
	s_lshl_b32 s0, s0, 7
	s_mov_b32 s1, 0
	s_waitcnt vmcnt(0)
	v_lshlrev_b32_e32 v1, 16, v1
	v_lshlrev_b32_e32 v35, 16, v35
	v_mul_f32_e32 v107, v106, v35
	v_mul_f32_e32 v35, v105, v35
	v_lshlrev_b32_e32 v103, 16, v103
	v_fma_f32 v107, v105, v1, -v107
	v_fmac_f32_e32 v35, v106, v1
	v_lshlrev_b32_e32 v37, 16, v37
	ds_write2st64_b32 v108, v107, v35 offset0:32 offset1:33
	v_mul_f32_e32 v1, v106, v103
	v_mul_f32_e32 v35, v105, v103
	v_fma_f32 v1, v105, v37, -v1
	v_fmac_f32_e32 v35, v106, v37
	v_mul_f32_e32 v1, 0x3db504f3, v1
	v_mul_f32_e32 v35, 0x3db504f3, v35
	ds_write2st64_b32 v108, v1, v35 offset0:16 offset1:17
	ds_write2st64_b32 v108, v101, v101 offset1:1
	v_lshlrev_b32_e32 v37, 2, v116
	v_and_b32_e32 v37, 0xfffffe00, v37
	v_add_u32_e32 v37, 0x5000, v37
	v_lshlrev_b32_e32 v1, 16, v117
	v_lshlrev_b32_e32 v35, 16, v118
	ds_write2st64_b32 v108, v1, v35 offset0:48 offset1:49
	v_lshlrev_b32_e32 v1, 16, v119
	v_lshlrev_b32_e32 v35, 16, v120
	ds_write2st64_b32 v108, v1, v35 offset0:64 offset1:65
	v_add_u32_e32 v1, 0, v156
	v_lshl_add_u32 v35, v102, 2, 0
	s_waitcnt lgkmcnt(0)
	s_barrier
.LBB0_120:
	v_add_u32_e32 v101, s1, v1
	ds_read_b32 v102, v101 offset:12288
	v_add_u32_e32 v101, s1, v35
	ds_read_b128 v[106:109], v101
	ds_read_b128 v[110:113], v101 offset:16
	ds_read_b128 v[114:117], v101 offset:32
	ds_read_b128 v[118:121], v101 offset:48
	ds_read_b128 v[122:125], v101 offset:4096
	ds_read_b128 v[126:129], v101 offset:8192
	s_addk_i32 s1, 0x200
	s_cmpk_lg_i32 s1, 0x1000
	s_waitcnt lgkmcnt(6)
	v_mov_b32_e32 v105, v102
	s_waitcnt lgkmcnt(1)
	v_pk_mul_f32 v[122:123], v[102:103], v[122:123] op_sel_hi:[0,1]
	v_pk_fma_f32 v[26:27], v[26:27], v[106:107], v[122:123]
	s_waitcnt lgkmcnt(0)
	v_fma_f32 v103, v126, v26, 0
	v_fmac_f32_e32 v103, v127, v27
	v_pk_mul_f32 v[106:107], v[102:103], v[124:125] op_sel_hi:[0,1]
	v_pk_fma_f32 v[22:23], v[22:23], v[108:109], v[106:107]
	ds_read_b128 v[106:109], v101 offset:4112
	ds_read_b128 v[122:125], v101 offset:8208
	v_fmac_f32_e32 v103, v128, v22
	v_fmac_f32_e32 v103, v129, v23
	s_waitcnt lgkmcnt(1)
	v_pk_mul_f32 v[106:107], v[102:103], v[106:107] op_sel_hi:[0,1]
	v_pk_fma_f32 v[20:21], v[20:21], v[110:111], v[106:107]
	s_waitcnt lgkmcnt(0)
	v_fmac_f32_e32 v103, v122, v20
	v_fmac_f32_e32 v103, v123, v21
	v_pk_mul_f32 v[106:107], v[102:103], v[108:109] op_sel_hi:[0,1]
	v_pk_fma_f32 v[18:19], v[18:19], v[112:113], v[106:107]
	ds_read_b128 v[106:109], v101 offset:4128
	ds_read_b128 v[110:113], v101 offset:8224
	v_fmac_f32_e32 v103, v124, v18
	v_fmac_f32_e32 v103, v125, v19
	s_waitcnt lgkmcnt(1)
	v_pk_mul_f32 v[106:107], v[102:103], v[106:107] op_sel_hi:[0,1]
	v_pk_fma_f32 v[54:55], v[54:55], v[114:115], v[106:107]
	s_waitcnt lgkmcnt(0)
	v_fmac_f32_e32 v103, v110, v54
	v_fmac_f32_e32 v103, v111, v55
	v_pk_mul_f32 v[106:107], v[102:103], v[108:109] op_sel_hi:[0,1]
	v_pk_fma_f32 v[50:51], v[50:51], v[116:117], v[106:107]
	s_nop 0
	v_fmac_f32_e32 v103, v112, v50
	v_fmac_f32_e32 v103, v113, v51
	ds_read_b128 v[106:109], v101 offset:4144
	ds_read_b128 v[110:113], v101 offset:8240
	s_waitcnt lgkmcnt(1)
	v_pk_mul_f32 v[106:107], v[102:103], v[106:107] op_sel_hi:[0,1]
	v_pk_fma_f32 v[48:49], v[48:49], v[118:119], v[106:107]
	s_waitcnt lgkmcnt(0)
	v_fmac_f32_e32 v103, v110, v48
	v_fmac_f32_e32 v103, v111, v49
	v_pk_mul_f32 v[106:107], v[102:103], v[108:109] op_sel_hi:[0,1]
	v_pk_fma_f32 v[46:47], v[46:47], v[120:121], v[106:107]
	s_nop 0
	v_fmac_f32_e32 v103, v112, v46
	v_fmac_f32_e32 v103, v113, v47
	ds_read_b128 v[106:109], v101 offset:64
	ds_read_b128 v[110:113], v101 offset:4160
	ds_read_b128 v[114:117], v101 offset:8256
	s_waitcnt lgkmcnt(1)
	v_pk_mul_f32 v[110:111], v[102:103], v[110:111] op_sel_hi:[0,1]
	v_pk_fma_f32 v[78:79], v[78:79], v[106:107], v[110:111]
	s_waitcnt lgkmcnt(0)
	v_fmac_f32_e32 v103, v114, v78
	v_fmac_f32_e32 v103, v115, v79
	v_pk_mul_f32 v[106:107], v[102:103], v[112:113] op_sel_hi:[0,1]
	v_pk_fma_f32 v[74:75], v[74:75], v[108:109], v[106:107]
	s_nop 0
	v_fmac_f32_e32 v103, v116, v74
	v_fmac_f32_e32 v103, v117, v75
	ds_read_b128 v[106:109], v101 offset:80
	ds_read_b128 v[110:113], v101 offset:4176
	ds_read_b128 v[114:117], v101 offset:8272
	s_waitcnt lgkmcnt(1)
	v_pk_mul_f32 v[110:111], v[102:103], v[110:111] op_sel_hi:[0,1]
	v_pk_fma_f32 v[72:73], v[72:73], v[106:107], v[110:111]
	s_waitcnt lgkmcnt(0)
	v_pk_mul_f32 v[106:107], v[114:115], v[72:73]
	s_nop 0
	v_add_f32_e32 v103, v106, v103
	v_add_f32_e32 v103, v107, v103
	v_pk_mul_f32 v[106:107], v[102:103], v[112:113] op_sel_hi:[0,1]
	v_pk_fma_f32 v[70:71], v[70:71], v[108:109], v[106:107]
	s_nop 0
	v_pk_mul_f32 v[106:107], v[116:117], v[70:71]
	s_nop 0
	v_add_f32_e32 v103, v106, v103
	v_add_f32_e32 v103, v107, v103
	ds_read_b128 v[106:109], v101 offset:96
	ds_read_b128 v[110:113], v101 offset:4192
	ds_read_b128 v[114:117], v101 offset:8288
	s_waitcnt lgkmcnt(1)
	v_pk_mul_f32 v[110:111], v[102:103], v[110:111] op_sel_hi:[0,1]
	v_pk_fma_f32 v[98:99], v[98:99], v[106:107], v[110:111]
	s_waitcnt lgkmcnt(0)
	v_pk_mul_f32 v[106:107], v[114:115], v[98:99]
	s_nop 0
	v_add_f32_e32 v103, v106, v103
	v_add_f32_e32 v103, v107, v103
	v_pk_mul_f32 v[106:107], v[102:103], v[112:113] op_sel_hi:[0,1]
	v_pk_fma_f32 v[96:97], v[96:97], v[108:109], v[106:107]
	s_nop 0
	v_pk_mul_f32 v[106:107], v[116:117], v[96:97]
	s_nop 0
	v_add_f32_e32 v103, v106, v103
	v_add_f32_e32 v103, v107, v103
	ds_read_b128 v[106:109], v101 offset:112
	ds_read_b128 v[110:113], v101 offset:4208
	ds_read_b128 v[114:117], v101 offset:8304
	s_waitcnt lgkmcnt(2)
	v_mul_f32_e32 v100, v100, v108
	s_waitcnt lgkmcnt(1)
	v_pk_mul_f32 v[110:111], v[102:103], v[110:111] op_sel_hi:[0,1]
	v_pk_fma_f32 v[94:95], v[94:95], v[106:107], v[110:111]
	s_waitcnt lgkmcnt(0)
	v_pk_mul_f32 v[106:107], v[114:115], v[94:95]
	s_nop 0
	v_add_f32_e32 v101, v106, v103
	v_mul_f32_e32 v106, v102, v112
	v_mov_b32_e32 v112, v109
	v_pk_mul_f32 v[102:103], v[104:105], v[112:113]
	v_add_f32_e32 v110, v107, v101
	v_mov_b32_e32 v101, v102
	v_mov_b32_e32 v107, v103
	v_pk_add_f32 v[100:101], v[100:101], v[106:107]
	s_nop 0
	v_pk_mul_f32 v[102:103], v[116:117], v[100:101]
	v_mov_b32_e32 v104, v101
	v_add_f32_e32 v102, v102, v110
	v_add_f32_e32 v102, v103, v102
	v_add_u32_e32 v103, v1, v37
	v_add_u32_e32 v37, 0x800, v37
	ds_write_b32 v103, v102
	s_cbranch_scc1 .LBB0_120
	s_ashr_i32 s15, s14, 31
	s_lshl_b64 s[14:15], s[14:15], 11
	s_add_u32 s1, s10, s14
	s_addc_u32 s3, s11, s15
	s_lshl_b32 s9, s0, 1
	s_add_u32 s10, s1, s9
	s_addc_u32 s11, s3, 0
	s_lshl_b32 s0, s0, 2
	s_add_u32 s6, s6, s0
	s_addc_u32 s7, s7, 0
	s_lshl_b64 s[0:1], s[12:13], 2
	s_add_u32 s0, s4, s0
	s_addc_u32 s1, s5, s1
	v_lshlrev_b32_e32 v156, 2, v0
	v_lshl_add_u64 v[0:1], s[0:1], 0, v[156:157]
	s_mov_b64 s[0:1], 0x8996000
	v_lshl_add_u64 v[0:1], v[0:1], 0, s[0:1]
	v_lshl_add_u64 v[2:3], v[0:1], 0, v[2:3]
	global_store_dword v[2:3], v26, off nt
	v_lshl_add_u64 v[2:3], v[0:1], 0, v[4:5]
	global_store_dword v[2:3], v27, off nt
	v_lshl_add_u64 v[2:3], v[0:1], 0, v[6:7]
	global_store_dword v[2:3], v22, off nt
	v_lshl_add_u64 v[2:3], v[0:1], 0, v[8:9]
	global_store_dword v[2:3], v23, off nt
	v_lshl_add_u64 v[2:3], v[0:1], 0, v[10:11]
	global_store_dword v[2:3], v20, off nt
	v_lshl_add_u64 v[2:3], v[0:1], 0, v[12:13]
	global_store_dword v[2:3], v21, off nt
	v_lshl_add_u64 v[2:3], v[0:1], 0, v[14:15]
	global_store_dword v[2:3], v18, off nt
	v_lshl_add_u64 v[2:3], v[0:1], 0, v[16:17]
	global_store_dword v[2:3], v19, off nt
	v_lshl_add_u64 v[2:3], v[0:1], 0, v[24:25]
	global_store_dword v[2:3], v54, off nt
	v_lshl_add_u64 v[2:3], v[0:1], 0, v[28:29]
	global_store_dword v[2:3], v55, off nt
	v_lshl_add_u64 v[2:3], v[0:1], 0, v[30:31]
	global_store_dword v[2:3], v50, off nt
	v_lshl_add_u64 v[2:3], v[0:1], 0, v[32:33]
	global_store_dword v[2:3], v51, off nt
	v_lshl_add_u64 v[2:3], v[0:1], 0, v[38:39]
	global_store_dword v[2:3], v48, off nt
	v_lshl_add_u64 v[2:3], v[0:1], 0, v[40:41]
	global_store_dword v[2:3], v49, off nt
	v_lshl_add_u64 v[2:3], v[0:1], 0, v[42:43]
	global_store_dword v[2:3], v46, off nt
	v_lshl_add_u64 v[2:3], v[0:1], 0, v[44:45]
	global_store_dword v[2:3], v47, off nt
	v_lshl_add_u64 v[2:3], v[0:1], 0, v[52:53]
	global_store_dword v[2:3], v78, off nt
	v_lshl_add_u64 v[2:3], v[0:1], 0, v[56:57]
	global_store_dword v[2:3], v79, off nt
	v_lshl_add_u64 v[2:3], v[0:1], 0, v[58:59]
	global_store_dword v[2:3], v74, off nt
	v_lshl_add_u64 v[2:3], v[0:1], 0, v[60:61]
	global_store_dword v[2:3], v75, off nt
	v_lshl_add_u64 v[2:3], v[0:1], 0, v[62:63]
	global_store_dword v[2:3], v72, off nt
	v_lshl_add_u64 v[2:3], v[0:1], 0, v[64:65]
	global_store_dword v[2:3], v73, off nt
	v_lshl_add_u64 v[2:3], v[0:1], 0, v[66:67]
	global_store_dword v[2:3], v70, off nt
	v_lshl_add_u64 v[2:3], v[0:1], 0, v[68:69]
	global_store_dword v[2:3], v71, off nt
	v_lshl_add_u64 v[2:3], v[0:1], 0, v[76:77]
	global_store_dword v[2:3], v98, off nt
	v_lshl_add_u64 v[2:3], v[0:1], 0, v[80:81]
	global_store_dword v[2:3], v99, off nt
	v_lshl_add_u64 v[2:3], v[0:1], 0, v[82:83]
	global_store_dword v[2:3], v96, off nt
	v_lshl_add_u64 v[2:3], v[0:1], 0, v[84:85]
	global_store_dword v[2:3], v97, off nt
	v_lshl_add_u64 v[2:3], v[0:1], 0, v[86:87]
	global_store_dword v[2:3], v94, off nt
	v_lshl_add_u64 v[2:3], v[0:1], 0, v[88:89]
	global_store_dword v[2:3], v95, off nt
	v_lshl_add_u64 v[2:3], v[0:1], 0, v[90:91]
	v_lshl_add_u64 v[0:1], v[0:1], 0, v[92:93]
	v_lshlrev_b32_e32 v8, 2, v34
	global_store_dword v[2:3], v100, off nt
	global_store_dword v[0:1], v101, off nt
	s_waitcnt lgkmcnt(0)
	s_barrier
	global_load_dword v9, v8, s[6:7] nt
	global_load_dword v10, v8, s[6:7] offset:256 nt
	v_lshlrev_b32_e32 v0, 11, v36
	v_add3_u32 v6, 0, v0, v8
	ds_read2st64_b32 v[0:1], v6 offset0:80 offset1:81
	ds_read2st64_b32 v[2:3], v6 offset0:82 offset1:83
	ds_read2st64_b32 v[4:5], v6 offset0:84 offset1:85
	ds_read2st64_b32 v[6:7], v6 offset0:86 offset1:87
	v_ashrrev_i32_e32 v37, 31, v36
	s_waitcnt lgkmcnt(3)
	v_add_f32_e32 v0, 0, v0
	v_add_f32_e32 v1, 0, v1
	s_waitcnt lgkmcnt(2)
	v_add_f32_e32 v0, v0, v2
	v_add_f32_e32 v1, v1, v3
	s_waitcnt lgkmcnt(1)
	v_add_f32_e32 v0, v0, v4
	v_add_f32_e32 v1, v1, v5
	s_waitcnt lgkmcnt(0)
	v_add_f32_e32 v2, v0, v6
	v_add_f32_e32 v6, v1, v7
	v_mul_f32_e32 v0, v6, v6
	v_fmac_f32_e32 v0, v2, v2
	v_lshlrev_b32_e32 v156, 1, v34
	s_nop 0
	v_add_f32_dpp v0, v0, v0 quad_perm:[1,0,3,2] row_mask:0xf bank_mask:0xf bound_ctrl:1
	s_nop 1
	v_add_f32_dpp v0, v0, v0 quad_perm:[2,3,0,1] row_mask:0xf bank_mask:0xf bound_ctrl:1
	s_nop 1
	v_add_f32_dpp v0, v0, v0 row_half_mirror row_mask:0xf bank_mask:0xf bound_ctrl:1
	s_nop 1
	v_add_f32_dpp v3, v0, v0 row_mirror row_mask:0xf bank_mask:0xf bound_ctrl:1
	s_nop 0
	v_readlane_b32 s1, v3, 16
	v_readlane_b32 s0, v3, 0
	s_nop 0
	v_mov_b32_e32 v0, s1
	v_add_f32_e32 v4, s0, v0
	v_lshlrev_b32_e32 v0, 9, v36
	v_add3_u32 v0, 0, v0, v8
	ds_read2st64_b32 v[0:1], v0 offset0:64 offset1:65
	v_readlane_b32 s1, v3, 48
	v_readlane_b32 s0, v3, 32
	s_waitcnt lgkmcnt(0)
	v_mul_f32_e32 v5, 0xbfb8aa3b, v0
	v_mov_b32_e32 v3, s1
	v_exp_f32_e32 v5, v5
	v_add_f32_e32 v3, s0, v3
	v_add_f32_e32 v3, v4, v3
	v_fmamk_f32 v3, v3, 0x3c000000, v194
	v_rsq_f32_e32 v7, v3
	v_add_f32_e32 v3, 1.0, v5
	v_rcp_f32_e32 v3, v3
	v_mul_f32_e32 v8, 0xbfb8aa3b, v1
	v_mul_f32_e32 v2, v2, v7
	v_exp_f32_e32 v8, v8
	v_mul_f32_e32 v0, v0, v3
	s_mov_b64 s[0:1], 0x1af00000
	v_add_f32_e32 v8, 1.0, v8
	v_rcp_f32_e32 v8, v8
	s_waitcnt vmcnt(1)
	v_mul_f32_e32 v2, v9, v2
	v_mul_f32_e32 v0, v0, v2
	v_bfe_u32 v2, v0, 16, 1
	v_add3_u32 v0, v0, v2, s54
	v_lshlrev_b64 v[2:3], 11, v[36:37]
	v_lshl_add_u64 v[2:3], s[10:11], 0, v[2:3]
	v_lshl_add_u64 v[2:3], v[2:3], 0, v[156:157]
	v_lshl_add_u64 v[4:5], v[2:3], 0, s[0:1]
	v_add_co_u32_e32 v2, vcc, s73, v2
	v_mul_f32_e32 v1, v1, v8
	s_nop 0
	v_addc_co_u32_e32 v3, vcc, 0, v3, vcc
	global_store_short_d16_hi v[2:3], v0, off
	v_mul_f32_e32 v0, v6, v7
	s_waitcnt vmcnt(1)
	v_mul_f32_e32 v0, v10, v0
	v_mul_f32_e32 v0, v0, v1
	v_readlane_b32 s0, v249, 36
	v_bfe_u32 v1, v0, 16, 1
	s_add_i32 s2, s2, s0
	v_add3_u32 v0, v0, v1, s54
	s_cmpk_gt_i32 s2, 0x1ff
	global_store_short_d16_hi v[4:5], v0, off offset:128
	s_barrier
	v_readlane_b32 s1, v249, 37
	s_cbranch_scc0 .LBB0_119

.LBB0_920:
	s_mov_b64 s[0:1], s[58:59]
	s_load_dwordx2 s[18:19], s[0:1], 0x158
	s_mov_b64 s[0:1], s[58:59]
	s_mov_b64 s[4:5], s[58:59]
	s_load_dwordx2 s[0:1], s[0:1], 0x18
	s_mov_b64 s[8:9], s[58:59]
	s_load_dwordx2 s[4:5], s[4:5], 0x150
	s_lshl_b32 s3, s2, 1
	s_load_dwordx2 s[10:11], s[8:9], 0x90
	s_mov_b64 s[8:9], s[58:59]
	s_and_b32 s3, s3, -8
	s_load_dwordx2 s[14:15], s[8:9], 0x158
	v_mbcnt_lo_u32_b32 v102, -1, 0
	v_mbcnt_hi_u32_b32 v102, -1, v102
	s_add_i32 s16, s3, 0x4000
	v_add_u32_e32 v1, s61, v102
	s_ashr_i32 s3, s2, 31
	s_lshl_b64 s[12:13], s[2:3], 14
	s_lshl_b64 s[8:9], s[2:3], 16
	v_ashrrev_i32_e32 v94, 2, v1
	s_waitcnt lgkmcnt(0)
	s_add_u32 s0, s0, s8
	v_and_b32_e32 v0, 0x7f, v1
	v_and_b32_e32 v98, 0xffffffe0, v94
	s_addc_u32 s1, s1, s9
	v_lshlrev_b32_e32 v156, 2, v0
	v_or_b32_e32 v4, 1, v98
	v_or_b32_e32 v6, 2, v98
	v_or_b32_e32 v8, 3, v98
	v_or_b32_e32 v10, 4, v98
	v_or_b32_e32 v12, 5, v98
	v_or_b32_e32 v14, 6, v98
	v_or_b32_e32 v16, 7, v98
	v_lshl_add_u64 v[90:91], s[0:1], 0, v[156:157]
	v_ashrrev_i32_e32 v99, 31, v98
	v_ashrrev_i32_e32 v5, 31, v4
	v_ashrrev_i32_e32 v7, 31, v6
	v_ashrrev_i32_e32 v9, 31, v8
	v_ashrrev_i32_e32 v11, 31, v10
	v_ashrrev_i32_e32 v13, 31, v12
	v_ashrrev_i32_e32 v15, 31, v14
	v_ashrrev_i32_e32 v17, 31, v16
	s_lshl_b32 s0, s2, 7
	v_lshlrev_b64 v[2:3], 9, v[98:99]
	v_lshlrev_b64 v[4:5], 9, v[4:5]
	v_lshlrev_b64 v[6:7], 9, v[6:7]
	v_lshlrev_b64 v[8:9], 9, v[8:9]
	v_lshlrev_b64 v[10:11], 9, v[10:11]
	v_lshlrev_b64 v[12:13], 9, v[12:13]
	v_lshlrev_b64 v[14:15], 9, v[14:15]
	v_lshlrev_b64 v[16:17], 9, v[16:17]
	s_and_b32 s0, s0, 0x180
	v_lshl_add_u64 v[18:19], v[90:91], 0, v[2:3]
	v_lshl_add_u64 v[20:21], v[90:91], 0, v[4:5]
	v_lshl_add_u64 v[22:23], v[90:91], 0, v[6:7]
	v_lshl_add_u64 v[24:25], v[90:91], 0, v[8:9]
	v_lshl_add_u64 v[28:29], v[90:91], 0, v[10:11]
	v_lshl_add_u64 v[30:31], v[90:91], 0, v[12:13]
	v_lshl_add_u64 v[32:33], v[90:91], 0, v[14:15]
	v_lshl_add_u64 v[34:35], v[90:91], 0, v[16:17]
	s_lshl_b32 s1, s0, 1
	global_load_dword v26, v[18:19], off nt
	global_load_dword v27, v[20:21], off nt
	s_nop 0
	global_load_dword v22, v[22:23], off nt
	s_nop 0
	global_load_dword v23, v[24:25], off nt
	global_load_dword v20, v[28:29], off nt
	global_load_dword v21, v[30:31], off nt
	global_load_dword v18, v[32:33], off nt
	global_load_dword v19, v[34:35], off nt
	v_or_b32_e32 v24, 8, v98
	v_or_b32_e32 v28, 9, v98
	v_or_b32_e32 v30, 10, v98
	v_or_b32_e32 v32, 11, v98
	v_or_b32_e32 v34, 12, v98
	s_add_u32 s8, s18, s1
	v_ashrrev_i32_e32 v25, 31, v24
	v_ashrrev_i32_e32 v29, 31, v28
	v_ashrrev_i32_e32 v31, 31, v30
	v_ashrrev_i32_e32 v33, 31, v32
	v_ashrrev_i32_e32 v35, 31, v34
	v_or_b32_e32 v36, 13, v98
	v_or_b32_e32 v38, 14, v98
	v_or_b32_e32 v40, 15, v98
	s_addc_u32 s9, s19, 0
	v_lshlrev_b32_e32 v72, 1, v0
	v_mov_b32_e32 v73, v157
	v_lshlrev_b64 v[24:25], 9, v[24:25]
	v_lshlrev_b64 v[28:29], 9, v[28:29]
	v_lshlrev_b64 v[30:31], 9, v[30:31]
	v_lshlrev_b64 v[32:33], 9, v[32:33]
	v_lshlrev_b64 v[34:35], 9, v[34:35]
	v_ashrrev_i32_e32 v37, 31, v36
	v_ashrrev_i32_e32 v39, 31, v38
	v_ashrrev_i32_e32 v41, 31, v40
	v_lshl_add_u64 v[72:73], s[8:9], 0, v[72:73]
	v_ashrrev_i32_e32 v76, 7, v1
	v_lshl_add_u64 v[42:43], v[90:91], 0, v[24:25]
	v_lshl_add_u64 v[44:45], v[90:91], 0, v[28:29]
	v_lshl_add_u64 v[46:47], v[90:91], 0, v[30:31]
	v_lshl_add_u64 v[48:49], v[90:91], 0, v[32:33]
	v_lshl_add_u64 v[52:53], v[90:91], 0, v[34:35]
	v_lshlrev_b64 v[36:37], 9, v[36:37]
	v_lshlrev_b64 v[38:39], 9, v[38:39]
	v_lshlrev_b64 v[40:41], 9, v[40:41]
	v_lshl_add_u64 v[72:73], v[72:73], 0, s[46:47]
	v_add_u32_e32 v76, s16, v76
	v_add_u32_e32 v88, 0x200, v1
	v_lshl_add_u64 v[54:55], v[90:91], 0, v[36:37]
	v_lshl_add_u64 v[56:57], v[90:91], 0, v[38:39]
	v_lshl_add_u64 v[58:59], v[90:91], 0, v[40:41]
	global_load_dword v50, v[42:43], off nt
	global_load_dword v51, v[44:45], off nt
	s_nop 0
	global_load_dword v46, v[46:47], off nt
	s_nop 0
	global_load_dword v47, v[48:49], off nt
	global_load_dword v44, v[52:53], off nt
	global_load_dword v45, v[54:55], off nt
	global_load_dword v42, v[56:57], off nt
	global_load_dword v43, v[58:59], off nt
	v_or_b32_e32 v48, 16, v98
	v_or_b32_e32 v52, 17, v98
	v_mad_i64_i32 v[76:77], s[8:9], v76, s83, v[72:73]
	v_ashrrev_i32_e32 v88, 7, v88
	v_ashrrev_i32_e32 v49, 31, v48
	v_ashrrev_i32_e32 v53, 31, v52
	v_or_b32_e32 v54, 18, v98
	v_or_b32_e32 v56, 19, v98
	v_or_b32_e32 v58, 20, v98
	v_or_b32_e32 v60, 21, v98
	v_or_b32_e32 v62, 22, v98
	v_or_b32_e32 v64, 23, v98
	v_add_co_u32_e32 v86, vcc, s72, v76
	v_add_u32_e32 v88, s16, v88
	v_lshlrev_b64 v[48:49], 9, v[48:49]
	v_lshlrev_b64 v[52:53], 9, v[52:53]
	v_ashrrev_i32_e32 v55, 31, v54
	v_ashrrev_i32_e32 v57, 31, v56
	v_ashrrev_i32_e32 v59, 31, v58
	v_ashrrev_i32_e32 v61, 31, v60
	v_ashrrev_i32_e32 v63, 31, v62
	v_ashrrev_i32_e32 v65, 31, v64
	v_addc_co_u32_e32 v87, vcc, 0, v77, vcc
	v_mad_i64_i32 v[72:73], s[8:9], v88, s83, v[72:73]
	v_lshl_add_u64 v[66:67], v[90:91], 0, v[48:49]
	v_lshl_add_u64 v[68:69], v[90:91], 0, v[52:53]
	v_lshlrev_b64 v[54:55], 9, v[54:55]
	v_lshlrev_b64 v[56:57], 9, v[56:57]
	v_lshlrev_b64 v[58:59], 9, v[58:59]
	v_lshlrev_b64 v[60:61], 9, v[60:61]
	v_lshlrev_b64 v[62:63], 9, v[62:63]
	v_lshlrev_b64 v[64:65], 9, v[64:65]
	v_add_co_u32_e32 v88, vcc, s72, v72
	v_lshl_add_u64 v[70:71], v[90:91], 0, v[54:55]
	v_lshl_add_u64 v[74:75], v[90:91], 0, v[56:57]
	v_lshl_add_u64 v[78:79], v[90:91], 0, v[58:59]
	v_lshl_add_u64 v[80:81], v[90:91], 0, v[60:61]
	v_lshl_add_u64 v[82:83], v[90:91], 0, v[62:63]
	v_lshl_add_u64 v[84:85], v[90:91], 0, v[64:65]
	v_addc_co_u32_e32 v89, vcc, 0, v73, vcc
	global_load_ushort v99, v[86:87], off
	global_load_ushort v103, v[86:87], off offset:1024
	global_load_ushort v114, v[86:87], off offset:2048
	global_load_ushort v115, v[88:89], off
	global_load_ushort v116, v[88:89], off offset:1024
	global_load_ushort v117, v[88:89], off offset:2048
	global_load_ushort v118, v[72:73], off offset:3072
	global_load_ushort v119, v[76:77], off offset:3072
	s_nop 0
	global_load_dword v76, v[66:67], off nt
	global_load_dword v77, v[68:69], off nt
	global_load_dword v72, v[70:71], off nt
	global_load_dword v73, v[74:75], off nt
	s_nop 0
	global_load_dword v68, v[78:79], off nt
	global_load_dword v69, v[80:81], off nt
	global_load_dword v66, v[82:83], off nt
	global_load_dword v67, v[84:85], off nt
	v_or_b32_e32 v70, 24, v98
	v_or_b32_e32 v74, 25, v98
	v_or_b32_e32 v78, 26, v98
	v_ashrrev_i32_e32 v71, 31, v70
	v_ashrrev_i32_e32 v75, 31, v74
	v_ashrrev_i32_e32 v79, 31, v78
	v_or_b32_e32 v80, 27, v98
	v_or_b32_e32 v82, 28, v98
	v_or_b32_e32 v84, 29, v98
	v_or_b32_e32 v86, 30, v98
	v_or_b32_e32 v88, 31, v94
	v_lshlrev_b64 v[70:71], 9, v[70:71]
	v_lshlrev_b64 v[74:75], 9, v[74:75]
	v_lshlrev_b64 v[78:79], 9, v[78:79]
	v_ashrrev_i32_e32 v81, 31, v80
	v_ashrrev_i32_e32 v83, 31, v82
	v_ashrrev_i32_e32 v85, 31, v84
	v_ashrrev_i32_e32 v87, 31, v86
	v_ashrrev_i32_e32 v89, 31, v88
	v_lshl_add_u64 v[92:93], v[90:91], 0, v[70:71]
	v_lshl_add_u64 v[96:97], v[90:91], 0, v[74:75]
	v_lshl_add_u64 v[100:101], v[90:91], 0, v[78:79]
	v_lshlrev_b64 v[80:81], 9, v[80:81]
	v_lshlrev_b64 v[82:83], 9, v[82:83]
	v_lshlrev_b64 v[84:85], 9, v[84:85]
	v_lshlrev_b64 v[86:87], 9, v[86:87]
	v_lshlrev_b64 v[88:89], 9, v[88:89]
	v_lshl_add_u64 v[104:105], v[90:91], 0, v[80:81]
	v_lshl_add_u64 v[106:107], v[90:91], 0, v[82:83]
	v_lshl_add_u64 v[108:109], v[90:91], 0, v[84:85]
	v_lshl_add_u64 v[110:111], v[90:91], 0, v[86:87]
	v_lshl_add_u64 v[112:113], v[90:91], 0, v[88:89]
	global_load_dword v94, v[92:93], off nt
	global_load_dword v95, v[96:97], off nt
	s_nop 0
	global_load_dword v92, v[100:101], off nt
	global_load_dword v93, v[104:105], off nt
	global_load_dword v90, v[106:107], off nt
	global_load_dword v91, v[108:109], off nt
	global_load_dword v96, v[110:111], off nt
	s_nop 0
	global_load_dword v100, v[112:113], off nt
	s_lshl_b32 s1, s0, 2
	s_add_i32 s1, s1, 0
	v_add_u32_e32 v97, s1, v156
	v_add_u32_e32 v97, 0x22400, v97
	s_mov_b32 s1, 0
	v_lshl_add_u32 v98, v98, 2, 0
	s_waitcnt vmcnt(0)
	v_lshlrev_b32_e32 v99, 16, v99
	v_mul_f32_e32 v99, 0xbfb8aa3b, v99
	v_exp_f32_e32 v99, v99
	v_lshlrev_b32_e32 v101, 16, v103
	ds_read_b32 v103, v97
	v_lshlrev_b32_e32 v105, 16, v114
	v_add_f32_e32 v99, 1.0, v99
	v_lshlrev_b32_e32 v104, 16, v119
	v_mul_f32_e32 v107, 0xbfb8aa3b, v104
	v_exp_f32_e32 v107, v107
	v_rcp_f32_e32 v99, v99
	s_waitcnt lgkmcnt(0)
	v_sub_f32_e32 v106, 1.0, v103
	v_add_f32_e32 v107, 1.0, v107
	v_rcp_f32_e32 v107, v107
	v_fmac_f32_e32 v103, v106, v99
	v_lshlrev_b32_e32 v106, 2, v1
	v_add_u32_e32 v99, 0, v106
	ds_write_b32 v99, v103
	v_sub_f32_e32 v103, 1.0, v103
	ds_write_b32 v99, v103 offset:4096
	v_mul_f32_e32 v103, v107, v104
	ds_write_b32 v99, v103 offset:8192
	ds_write_b32 v99, v101 offset:12288
	ds_write_b32 v99, v105 offset:16384
	v_lshlrev_b32_e32 v101, 16, v115
	v_mul_f32_e32 v101, 0xbfb8aa3b, v101
	v_exp_f32_e32 v101, v101
	v_lshlrev_b32_e32 v104, 16, v118
	ds_read_b32 v97, v97
	v_mul_f32_e32 v105, 0xbfb8aa3b, v104
	v_add_f32_e32 v101, 1.0, v101
	v_rcp_f32_e32 v101, v101
	v_exp_f32_e32 v105, v105
	s_waitcnt lgkmcnt(0)
	v_sub_f32_e32 v108, 1.0, v97
	v_lshlrev_b32_e32 v103, 16, v116
	v_fmac_f32_e32 v97, v108, v101
	v_add_f32_e32 v101, 1.0, v105
	v_rcp_f32_e32 v101, v101
	ds_write_b32 v99, v97 offset:2048
	v_sub_f32_e32 v97, 1.0, v97
	ds_write_b32 v99, v97 offset:6144
	v_mul_f32_e32 v97, v101, v104
	v_lshlrev_b32_e32 v107, 16, v117
	ds_write_b32 v99, v97 offset:10240
	ds_write_b32 v99, v103 offset:14336
	ds_write_b32 v99, v107 offset:18432
	v_and_b32_e32 v97, 0xfffffe00, v106
	v_add_u32_e32 v99, 0, v156
	v_add_u32_e32 v103, 0x5000, v97
	s_waitcnt lgkmcnt(0)
	s_barrier
.LBB0_921:
	v_add_u32_e32 v97, s1, v99
	ds_read_b32 v128, v97 offset:12288
	v_add_u32_e32 v97, s1, v98
	ds_read_b128 v[104:107], v97
	ds_read_b128 v[108:111], v97 offset:16
	ds_read_b128 v[112:115], v97 offset:32
	ds_read_b128 v[116:119], v97 offset:48
	ds_read_b128 v[120:123], v97 offset:4096
	ds_read_b128 v[124:127], v97 offset:8192
	s_addk_i32 s1, 0x200
	s_cmpk_lg_i32 s1, 0x1000
	s_waitcnt lgkmcnt(1)
	v_pk_mul_f32 v[120:121], v[128:129], v[120:121] op_sel_hi:[0,1]
	v_pk_fma_f32 v[26:27], v[26:27], v[104:105], v[120:121]
	v_pk_mul_f32 v[104:105], v[128:129], v[122:123] op_sel_hi:[0,1]
	v_pk_fma_f32 v[22:23], v[22:23], v[106:107], v[104:105]
	ds_read_b128 v[104:107], v97 offset:4112
	ds_read_b128 v[120:123], v97 offset:8208
	s_waitcnt lgkmcnt(2)
	v_fma_f32 v101, v124, v26, 0
	v_fmac_f32_e32 v101, v125, v27
	v_fmac_f32_e32 v101, v126, v22
	s_waitcnt lgkmcnt(1)
	v_pk_mul_f32 v[104:105], v[128:129], v[104:105] op_sel_hi:[0,1]
	v_pk_fma_f32 v[20:21], v[20:21], v[108:109], v[104:105]
	v_pk_mul_f32 v[104:105], v[128:129], v[106:107] op_sel_hi:[0,1]
	v_pk_fma_f32 v[18:19], v[18:19], v[110:111], v[104:105]
	ds_read_b128 v[104:107], v97 offset:4128
	ds_read_b128 v[108:111], v97 offset:8224
	v_fmac_f32_e32 v101, v127, v23
	s_waitcnt lgkmcnt(2)
	v_fmac_f32_e32 v101, v120, v20
	v_fmac_f32_e32 v101, v121, v21
	v_fmac_f32_e32 v101, v122, v18
	s_waitcnt lgkmcnt(1)
	v_pk_mul_f32 v[104:105], v[128:129], v[104:105] op_sel_hi:[0,1]
	v_fmac_f32_e32 v101, v123, v19
	v_pk_fma_f32 v[50:51], v[50:51], v[112:113], v[104:105]
	v_pk_mul_f32 v[104:105], v[128:129], v[106:107] op_sel_hi:[0,1]
	s_waitcnt lgkmcnt(0)
	v_fmac_f32_e32 v101, v108, v50
	v_fmac_f32_e32 v101, v109, v51
	v_pk_fma_f32 v[46:47], v[46:47], v[114:115], v[104:105]
	s_nop 0
	v_fmac_f32_e32 v101, v110, v46
	v_fmac_f32_e32 v101, v111, v47
	ds_read_b128 v[104:107], v97 offset:4144
	ds_read_b128 v[108:111], v97 offset:8240
	s_waitcnt lgkmcnt(1)
	v_pk_mul_f32 v[104:105], v[128:129], v[104:105] op_sel_hi:[0,1]
	v_pk_fma_f32 v[44:45], v[44:45], v[116:117], v[104:105]
	v_pk_mul_f32 v[104:105], v[128:129], v[106:107] op_sel_hi:[0,1]
	s_waitcnt lgkmcnt(0)
	v_fmac_f32_e32 v101, v108, v44
	v_fmac_f32_e32 v101, v109, v45
	v_pk_fma_f32 v[42:43], v[42:43], v[118:119], v[104:105]
	s_nop 0
	v_fmac_f32_e32 v101, v110, v42
	v_fmac_f32_e32 v101, v111, v43
	ds_read_b128 v[104:107], v97 offset:64
	ds_read_b128 v[108:111], v97 offset:4160
	ds_read_b128 v[112:115], v97 offset:8256
	s_waitcnt lgkmcnt(1)
	v_pk_mul_f32 v[108:109], v[128:129], v[108:109] op_sel_hi:[0,1]
	v_pk_fma_f32 v[76:77], v[76:77], v[104:105], v[108:109]
	v_pk_mul_f32 v[104:105], v[128:129], v[110:111] op_sel_hi:[0,1]
	s_waitcnt lgkmcnt(0)
	v_fmac_f32_e32 v101, v112, v76
	v_fmac_f32_e32 v101, v113, v77
	v_pk_fma_f32 v[72:73], v[72:73], v[106:107], v[104:105]
	s_nop 0
	v_fmac_f32_e32 v101, v114, v72
	v_fmac_f32_e32 v101, v115, v73
	ds_read_b128 v[104:107], v97 offset:80
	ds_read_b128 v[108:111], v97 offset:4176
	ds_read_b128 v[112:115], v97 offset:8272
	s_waitcnt lgkmcnt(1)
	v_pk_mul_f32 v[108:109], v[128:129], v[108:109] op_sel_hi:[0,1]
	v_pk_fma_f32 v[68:69], v[68:69], v[104:105], v[108:109]
	s_waitcnt lgkmcnt(0)
	v_pk_mul_f32 v[104:105], v[112:113], v[68:69]
	s_nop 0
	v_add_f32_e32 v101, v104, v101
	v_add_f32_e32 v101, v105, v101
	v_pk_mul_f32 v[104:105], v[128:129], v[110:111] op_sel_hi:[0,1]
	v_pk_fma_f32 v[66:67], v[66:67], v[106:107], v[104:105]
	s_nop 0
	v_pk_mul_f32 v[104:105], v[114:115], v[66:67]
	s_nop 0
	v_add_f32_e32 v101, v104, v101
	v_add_f32_e32 v101, v105, v101
	ds_read_b128 v[104:107], v97 offset:96
	ds_read_b128 v[108:111], v97 offset:4192
	ds_read_b128 v[112:115], v97 offset:8288
	s_waitcnt lgkmcnt(1)
	v_pk_mul_f32 v[108:109], v[128:129], v[108:109] op_sel_hi:[0,1]
	v_pk_fma_f32 v[94:95], v[94:95], v[104:105], v[108:109]
	s_waitcnt lgkmcnt(0)
	v_pk_mul_f32 v[104:105], v[112:113], v[94:95]
	s_nop 0
	v_add_f32_e32 v101, v104, v101
	v_add_f32_e32 v101, v105, v101
	v_pk_mul_f32 v[104:105], v[128:129], v[110:111] op_sel_hi:[0,1]
	v_pk_fma_f32 v[92:93], v[92:93], v[106:107], v[104:105]
	s_nop 0
	v_pk_mul_f32 v[104:105], v[114:115], v[92:93]
	s_nop 0
	v_add_f32_e32 v101, v104, v101
	v_add_f32_e32 v101, v105, v101
	ds_read_b128 v[104:107], v97 offset:112
	ds_read_b128 v[108:111], v97 offset:4208
	ds_read_b128 v[112:115], v97 offset:8304
	s_waitcnt lgkmcnt(2)
	v_mul_f32_e32 v96, v96, v106
	s_waitcnt lgkmcnt(1)
	v_pk_mul_f32 v[108:109], v[128:129], v[108:109] op_sel_hi:[0,1]
	v_pk_fma_f32 v[90:91], v[90:91], v[104:105], v[108:109]
	s_waitcnt lgkmcnt(0)
	v_pk_mul_f32 v[104:105], v[112:113], v[90:91]
	s_nop 0
	v_add_f32_e32 v97, v104, v101
	v_mul_f32_e32 v104, v128, v110
	v_mov_b32_e32 v101, v128
	v_mov_b32_e32 v110, v107
	v_pk_mul_f32 v[100:101], v[100:101], v[110:111]
	v_add_f32_e32 v108, v105, v97
	v_mov_b32_e32 v97, v100
	v_mov_b32_e32 v105, v101
	v_pk_add_f32 v[96:97], v[96:97], v[104:105]
	s_nop 0
	v_pk_mul_f32 v[100:101], v[114:115], v[96:97]
	s_nop 0
	v_add_f32_e32 v100, v100, v108
	v_add_f32_e32 v100, v101, v100
	v_add_u32_e32 v101, v99, v103
	ds_write_b32 v101, v100
	v_add_u32_e32 v103, 0x800, v103
	v_mov_b32_e32 v100, v97
	s_cbranch_scc1 .LBB0_921
	s_ashr_i32 s17, s16, 31
	s_lshl_b64 s[8:9], s[16:17], 11
	s_add_u32 s1, s14, s8
	s_addc_u32 s3, s15, s9
	s_lshl_b32 s8, s0, 1
	s_add_u32 s14, s1, s8
	s_addc_u32 s15, s3, 0
	s_lshl_b32 s0, s0, 2
	s_add_u32 s10, s10, s0
	s_addc_u32 s11, s11, 0
	s_lshl_b64 s[0:1], s[12:13], 2
	s_add_u32 s0, s4, s0
	s_addc_u32 s1, s5, s1
	v_lshlrev_b32_e32 v156, 2, v0
	v_lshl_add_u64 v[98:99], s[0:1], 0, v[156:157]
	s_mov_b64 s[0:1], 0x6996000
	v_lshl_add_u64 v[98:99], v[98:99], 0, s[0:1]
	v_lshl_add_u64 v[2:3], v[98:99], 0, v[2:3]
	global_store_dword v[2:3], v26, off nt
	v_lshl_add_u64 v[2:3], v[98:99], 0, v[4:5]
	global_store_dword v[2:3], v27, off nt
	v_lshl_add_u64 v[2:3], v[98:99], 0, v[6:7]
	global_store_dword v[2:3], v22, off nt
	v_lshl_add_u64 v[2:3], v[98:99], 0, v[8:9]
	global_store_dword v[2:3], v23, off nt
	v_lshl_add_u64 v[2:3], v[98:99], 0, v[10:11]
	global_store_dword v[2:3], v20, off nt
	v_lshl_add_u64 v[2:3], v[98:99], 0, v[12:13]
	global_store_dword v[2:3], v21, off nt
	v_lshl_add_u64 v[2:3], v[98:99], 0, v[14:15]
	global_store_dword v[2:3], v18, off nt
	v_lshl_add_u64 v[2:3], v[98:99], 0, v[16:17]
	global_store_dword v[2:3], v19, off nt
	v_lshl_add_u64 v[2:3], v[98:99], 0, v[24:25]
	global_store_dword v[2:3], v50, off nt
	v_lshl_add_u64 v[2:3], v[98:99], 0, v[28:29]
	global_store_dword v[2:3], v51, off nt
	v_lshl_add_u64 v[2:3], v[98:99], 0, v[30:31]
	global_store_dword v[2:3], v46, off nt
	v_lshl_add_u64 v[2:3], v[98:99], 0, v[32:33]
	global_store_dword v[2:3], v47, off nt
	v_lshl_add_u64 v[2:3], v[98:99], 0, v[34:35]
	global_store_dword v[2:3], v44, off nt
	v_lshl_add_u64 v[2:3], v[98:99], 0, v[36:37]
	global_store_dword v[2:3], v45, off nt
	v_lshl_add_u64 v[2:3], v[98:99], 0, v[38:39]
	global_store_dword v[2:3], v42, off nt
	v_lshl_add_u64 v[2:3], v[98:99], 0, v[40:41]
	global_store_dword v[2:3], v43, off nt
	v_lshl_add_u64 v[2:3], v[98:99], 0, v[48:49]
	global_store_dword v[2:3], v76, off nt
	v_lshl_add_u64 v[2:3], v[98:99], 0, v[52:53]
	global_store_dword v[2:3], v77, off nt
	v_lshl_add_u64 v[2:3], v[98:99], 0, v[54:55]
	global_store_dword v[2:3], v72, off nt
	v_lshl_add_u64 v[2:3], v[98:99], 0, v[56:57]
	global_store_dword v[2:3], v73, off nt
	v_lshl_add_u64 v[2:3], v[98:99], 0, v[58:59]
	global_store_dword v[2:3], v68, off nt
	v_lshl_add_u64 v[2:3], v[98:99], 0, v[60:61]
	global_store_dword v[2:3], v69, off nt
	v_lshl_add_u64 v[2:3], v[98:99], 0, v[62:63]
	global_store_dword v[2:3], v66, off nt
	v_lshl_add_u64 v[2:3], v[98:99], 0, v[64:65]
	global_store_dword v[2:3], v67, off nt
	v_lshl_add_u64 v[2:3], v[98:99], 0, v[70:71]
	global_store_dword v[2:3], v94, off nt
	v_lshl_add_u64 v[2:3], v[98:99], 0, v[74:75]
	global_store_dword v[2:3], v95, off nt
	v_lshl_add_u64 v[2:3], v[98:99], 0, v[78:79]
	global_store_dword v[2:3], v92, off nt
	v_lshl_add_u64 v[2:3], v[98:99], 0, v[80:81]
	global_store_dword v[2:3], v93, off nt
	v_lshl_add_u64 v[2:3], v[98:99], 0, v[82:83]
	global_store_dword v[2:3], v90, off nt
	v_lshl_add_u64 v[2:3], v[98:99], 0, v[84:85]
	v_and_b32_e32 v100, 63, v102
	global_store_dword v[2:3], v91, off nt
	v_lshl_add_u64 v[2:3], v[98:99], 0, v[86:87]
	global_store_dword v[2:3], v96, off nt
	v_lshl_add_u64 v[2:3], v[98:99], 0, v[88:89]
	v_lshlrev_b32_e32 v10, 2, v100
	global_store_dword v[2:3], v97, off nt
	s_waitcnt lgkmcnt(0)
	s_barrier
	global_load_dword v11, v10, s[10:11] nt
	global_load_dword v12, v10, s[10:11] offset:256 nt
	v_ashrrev_i32_e32 v0, 6, v1
	v_lshlrev_b32_e32 v1, 11, v0
	v_add3_u32 v1, 0, v1, v10
	ds_read2st64_b32 v[2:3], v1 offset0:80 offset1:81
	ds_read2st64_b32 v[4:5], v1 offset0:82 offset1:83
	ds_read2st64_b32 v[6:7], v1 offset0:84 offset1:85
	ds_read2st64_b32 v[8:9], v1 offset0:86 offset1:87
	v_lshlrev_b32_e32 v156, 1, v100
	s_waitcnt lgkmcnt(3)
	v_add_f32_e32 v1, 0, v2
	v_add_f32_e32 v2, 0, v3
	s_waitcnt lgkmcnt(2)
	v_add_f32_e32 v2, v2, v5
	v_add_f32_e32 v1, v1, v4
	s_waitcnt lgkmcnt(1)
	v_add_f32_e32 v2, v2, v7
	v_add_f32_e32 v1, v1, v6
	s_waitcnt lgkmcnt(0)
	v_add_f32_e32 v6, v2, v9
	v_add_f32_e32 v1, v1, v8
	v_mul_f32_e32 v2, v6, v6
	v_fmac_f32_e32 v2, v1, v1
	s_add_i32 s2, s2, s50
	s_cmpk_gt_i32 s2, 0x1ff
	v_add_f32_dpp v2, v2, v2 quad_perm:[1,0,3,2] row_mask:0xf bank_mask:0xf bound_ctrl:1
	s_nop 1
	v_add_f32_dpp v2, v2, v2 quad_perm:[2,3,0,1] row_mask:0xf bank_mask:0xf bound_ctrl:1
	s_nop 1
	v_add_f32_dpp v2, v2, v2 row_half_mirror row_mask:0xf bank_mask:0xf bound_ctrl:1
	s_nop 1
	v_add_f32_dpp v4, v2, v2 row_mirror row_mask:0xf bank_mask:0xf bound_ctrl:1
	s_nop 0
	v_readlane_b32 s1, v4, 16
	v_readlane_b32 s0, v4, 0
	s_nop 0
	v_mov_b32_e32 v2, s1
	v_add_f32_e32 v5, s0, v2
	v_lshlrev_b32_e32 v2, 9, v0
	v_add3_u32 v2, 0, v2, v10
	ds_read2st64_b32 v[2:3], v2 offset0:64 offset1:65
	v_readlane_b32 s1, v4, 48
	v_readlane_b32 s0, v4, 32
	s_waitcnt lgkmcnt(0)
	v_mul_f32_e32 v7, 0xbfb8aa3b, v2
	v_mov_b32_e32 v4, s1
	v_exp_f32_e32 v7, v7
	v_add_f32_e32 v4, s0, v4
	v_add_f32_e32 v4, v5, v4
	v_fmamk_f32 v4, v4, 0x3c000000, v194
	v_rsq_f32_e32 v8, v4
	v_add_f32_e32 v4, 1.0, v7
	v_rcp_f32_e32 v4, v4
	v_mul_f32_e32 v7, 0xbfb8aa3b, v3
	v_mul_f32_e32 v1, v1, v8
	v_exp_f32_e32 v7, v7
	v_mul_f32_e32 v2, v2, v4
	v_add_f32_e32 v7, 1.0, v7
	v_rcp_f32_e32 v7, v7
	s_waitcnt vmcnt(1)
	v_mul_f32_e32 v1, v11, v1
	v_mul_f32_e32 v1, v2, v1
	v_bfe_u32 v2, v1, 16, 1
	v_add3_u32 v2, v1, v2, s54
	v_ashrrev_i32_e32 v1, 31, v0
	v_lshlrev_b64 v[0:1], 11, v[0:1]
	v_lshl_add_u64 v[0:1], s[14:15], 0, v[0:1]
	v_lshl_add_u64 v[0:1], v[0:1], 0, v[156:157]
	v_lshl_add_u64 v[4:5], v[0:1], 0, s[22:23]
	v_add_co_u32_e32 v0, vcc, s73, v0
	s_nop 1
	v_addc_co_u32_e32 v1, vcc, 0, v1, vcc
	global_store_short_d16_hi v[0:1], v2, off offset:1024
	v_mul_f32_e32 v0, v6, v8
	s_waitcnt vmcnt(1)
	v_mul_f32_e32 v0, v12, v0
	v_mul_f32_e32 v1, v3, v7
	v_mul_f32_e32 v0, v0, v1
	v_bfe_u32 v1, v0, 16, 1
	v_add3_u32 v0, v0, v1, s54
	global_store_short_d16_hi v[4:5], v0, off offset:128
	s_barrier
	s_cbranch_scc0 .LBB0_920
